# P4 compressed-branch max/sum reduction across row groups: four serial ds_bpermute round trips per token iteration replaced by v_permlane16/32_swap pairs
# baseline (speedup 1.0000x reference)
.LBB0_441:
	s_or_b64 exec, exec, s[14:15]
	v_mov_b32_e32 v3, v1
	v_mov_b32_e32 v249, v1
	s_nop 1
	v_permlane16_swap_b32_e32 v3, v249
	s_waitcnt vmcnt(0)
	v_mov_b32_e32 v19, 0
	v_lshlrev_b64 v[202:203], 10, v[110:111]
	v_mov_b32_e32 v18, v19
	s_waitcnt lgkmcnt(0)
	v_max_f32_e32 v3, v3, v249
	v_mov_b32_e32 v12, v3
	v_mov_b32_e32 v249, v3
	s_nop 1
	v_permlane32_swap_b32_e32 v12, v249
	v_mov_b32_e32 v17, v19
	v_mov_b32_e32 v16, v19
	v_mov_b32_e32 v23, v19
	v_mov_b32_e32 v22, v19
	s_waitcnt lgkmcnt(0)
	v_max_f32_e32 v3, v12, v249
	v_sub_f32_e32 v1, v1, v3
	v_exp_f32_e32 v12, v1
	v_mov_b32_e32 v21, v19
	v_mov_b32_e32 v20, v19
	v_mov_b32_e32 v27, v19
	v_mul_f32_e32 v1, v2, v12
	v_mov_b32_e32 v249, v1
	v_mov_b32_e32 v250, v1
	s_nop 1
	v_permlane16_swap_b32_e32 v249, v250
	v_mov_b32_e32 v26, v19
	v_mov_b32_e32 v25, v19
	v_mov_b32_e32 v24, v19
	v_mov_b32_e32 v15, v19
	s_waitcnt lgkmcnt(0)
	v_add_f32_e32 v1, v249, v250
	v_mov_b32_e32 v2, v1
	v_mov_b32_e32 v249, v1
	s_nop 1
	v_permlane32_swap_b32_e32 v2, v249
	v_mov_b32_e32 v14, v19
	v_mov_b32_e32 v13, v19
	v_mov_b32_e32 v12, v19
	ds_write2st64_b32 v213, v0, v0 offset1:1
	ds_write2st64_b32 v213, v0, v0 offset0:2 offset1:3
	ds_write2st64_b32 v213, v0, v0 offset0:4 offset1:5
	ds_write2st64_b32 v213, v0, v0 offset0:6 offset1:7
	ds_write2st64_b32 v213, v0, v0 offset0:8 offset1:9
	ds_write2st64_b32 v213, v0, v0 offset0:10 offset1:11
	ds_write2st64_b32 v213, v0, v0 offset0:12 offset1:13
	ds_write2st64_b32 v213, v0, v0 offset0:14 offset1:15
	s_and_saveexec_b64 s[14:15], s[12:13]
	s_cbranch_execz .LBB0_503
	global_load_dwordx4 v[56:59], v[172:173], off
	global_load_dwordx4 v[52:55], v[172:173], off offset:1024
	global_load_dwordx4 v[48:51], v[172:173], off offset:2048
	global_load_dwordx4 v[40:43], v[172:173], off offset:3072
	global_load_dwordx4 v[44:47], v[174:175], off
	global_load_dwordx4 v[36:39], v[176:177], off
	global_load_dwordx4 v[32:35], v[178:179], off
	global_load_dwordx4 v[28:31], v[180:181], off
	s_waitcnt lgkmcnt(8)
	v_add_f32_e32 v1, v2, v249
	v_log_f32_e32 v2, v1
	v_mov_b32_e32 v12, 0
	v_cmp_lt_f32_e32 vcc, 0, v1
	s_mov_b32 s22, 0
	v_add_f32_e32 v2, v3, v2
	v_cndmask_b32_e32 v111, v221, v2, vcc
	s_movk_i32 s12, 0x1000
	s_movk_i32 s23, 0x7f
	s_mov_b64 s[16:17], 0
	v_mov_b32_e32 v116, v218
	v_mov_b32_e32 v13, v12
	v_mov_b32_e32 v14, v12
	v_mov_b32_e32 v15, v12
	v_mov_b32_e32 v24, v12
	v_mov_b32_e32 v25, v12
	v_mov_b32_e32 v26, v12
	v_mov_b32_e32 v27, v12
	v_mov_b32_e32 v20, v12
	v_mov_b32_e32 v21, v12
	v_mov_b32_e32 v22, v12
	v_mov_b32_e32 v23, v12
	v_mov_b32_e32 v16, v12
	v_mov_b32_e32 v17, v12
	v_mov_b32_e32 v18, v12
	v_mov_b32_e32 v19, v12
	s_branch .LBB0_445
